# weight transposes (w_out, gate, ffn_up, ffn_down) moved from phase 0 into the scan phase loader waves, half item per loader iteration
# speedup vs baseline: 1.0082x; 1.0069x over previous
.LBB0_101:
	s_or_b64 exec, exec, s[34:35]
	s_lshl_b64 s[34:35], s[22:23], 22
	s_and_saveexec_b64 s[50:51], s[42:43]
	s_branch .LBB0_104
	s_load_dwordx2 s[0:1], s[28:29], 0xa8
	s_lshl_b64 s[18:19], s[34:35], 2
	v_lshl_add_u64 v[0:1], s[34:35], 1, v[18:19]
	v_lshlrev_b32_e32 v35, 5, v10
	s_mov_b64 s[52:53], 0
	s_waitcnt lgkmcnt(0)
	s_add_u32 s18, s0, s18
	s_addc_u32 s19, s1, s19
	s_lshl_b32 s0, s8, 5
	v_lshl_add_u64 v[2:3], s[18:19], 0, v[156:157]
	v_mov_b32_e32 v37, v10

.LBB0_104:
	s_or_b64 exec, exec, s[50:51]
	s_and_saveexec_b64 s[50:51], s[44:45]
	s_branch .LBB0_112
	s_load_dwordx4 s[56:59], s[28:29], 0xb0
	s_lshl_b64 s[52:53], s[22:23], 24
	s_lshl_b64 s[0:1], s[30:31], 2
	v_mov_b32_e32 v37, v157
	v_lshlrev_b32_e32 v35, 5, v10
	s_waitcnt lgkmcnt(0)
	s_add_u32 s0, s56, s0
	s_addc_u32 s1, s57, s1
	s_lshl_b64 s[18:19], s[22:23], 26
	s_add_u32 s18, s58, s18
	s_addc_u32 s19, s59, s19
	s_cmp_lg_u64 s[56:57], 0
	s_cselect_b64 s[56:57], -1, 0
	v_lshl_add_u64 v[38:39], s[0:1], 0, v[36:37]
	s_lshl_b64 s[0:1], s[22:23], 25
	s_mov_b64 s[54:55], 0
	v_lshl_add_u64 v[40:41], s[18:19], 0, v[156:157]
	v_lshl_add_u64 v[42:43], v[20:21], 0, s[0:1]
	s_lshl_b32 s0, s8, 5
	v_mov_b32_e32 v53, v35
	v_mov_b32_e32 v58, v10
	s_branch .LBB0_108

.LBB0_112:
	s_or_b64 exec, exec, s[50:51]
	s_and_saveexec_b64 s[50:51], s[42:43]
	s_branch .LBB0_118
	s_load_dwordx4 s[52:55], s[28:29], 0xc8
	s_lshl_b64 s[0:1], s[30:31], 2
	v_mov_b32_e32 v37, v157
	s_mov_b64 s[30:31], 0
	v_lshl_add_u64 v[40:41], s[34:35], 1, v[24:25]
	s_waitcnt lgkmcnt(0)
	s_add_u32 s0, s52, s0
	s_addc_u32 s1, s53, s1
	s_lshl_b64 s[18:19], s[34:35], 2
	s_add_u32 s18, s54, s18
	s_addc_u32 s19, s55, s19
	s_cmp_lg_u64 s[52:53], 0
	s_cselect_b64 s[52:53], -1, 0
	v_lshl_add_u64 v[36:37], s[0:1], 0, v[36:37]
	v_lshl_add_u64 v[38:39], s[18:19], 0, v[156:157]
	v_lshlrev_b32_e32 v35, 5, v10
	s_lshl_b32 s0, s8, 5
	v_mov_b32_e32 v50, v10
	s_branch .LBB0_116

.LBB0_190:
	v_readfirstlane_b32 s13, v160
	s_ashr_i32 s13, s13, 6
	s_cmp_gt_i32 s13, 3
	s_mov_b64 s[14:15], -1
	s_cbranch_scc0 .LBB0_219
	s_load_dwordx2 s[50:51], s[28:29], 0xa8
	s_load_dwordx2 s[52:53], s[28:29], 0xd0
	s_load_dwordx2 s[58:59], s[28:29], 0xc0
	s_load_dwordx2 s[60:61], s[28:29], 0xb8
	s_load_dwordx2 s[62:63], s[28:29], 0xc8
	s_load_dwordx2 s[64:65], s[28:29], 0xb0
	s_load_dwordx2 s[66:67], s[28:29], 0xf0
	v_readlane_b32 s56, v254, 22
	v_lshrrev_b32_e32 v222, 3, v197
	v_and_b32_e32 v223, 7, v197
	v_lshlrev_b32_e32 v217, 2, v222
	v_mul_u32_u24_e32 v218, 33, v222
	v_lshl_add_u32 v218, v223, 2, v218
	v_lshlrev_b32_e32 v218, 2, v218
	v_and_b32_e32 v223, 3, v197
	v_lshrrev_b32_e32 v222, 2, v197
	v_mul_u32_u24_e32 v219, 0x108, v223
	v_add_lshl_u32 v219, v219, v222, 2
	s_sub_u32 s57, s13, 4
	s_mul_i32 s55, s57, 0x1080
	s_add_u32 s55, s55, 0x16000
	v_add_u32_e32 v218, s55, v218
	v_add_u32_e32 v219, s55, v219
	v_readlane_b32 s55, v253, 0
	s_lshl_b32 s55, s55, 2
	s_add_u32 s55, s55, s57
	s_waitcnt lgkmcnt(0)
	s_lshl_b32 s57, s56, 24
	s_add_u32 s50, s50, s57
	s_addc_u32 s51, s51, 0
	v_writelane_b32 v224, s50, 0
	v_writelane_b32 v224, s51, 1
	s_lshl_b32 s57, s56, 24
	s_add_u32 s52, s52, s57
	s_addc_u32 s53, s53, 0
	v_writelane_b32 v224, s52, 2
	v_writelane_b32 v224, s53, 3
	s_lshl_b32 s57, s56, 26
	s_add_u32 s58, s58, s57
	s_addc_u32 s59, s59, 0
	v_writelane_b32 v224, s58, 4
	v_writelane_b32 v224, s59, 5
	s_lshl_b32 s57, s56, 26
	s_add_u32 s60, s60, s57
	s_addc_u32 s61, s61, 0
	v_writelane_b32 v224, s60, 6
	v_writelane_b32 v224, s61, 7
	s_lshl_b32 s57, s56, 13
	s_add_u32 s62, s62, s57
	s_addc_u32 s63, s63, 0
	v_writelane_b32 v224, s62, 8
	v_writelane_b32 v224, s63, 9
	s_lshl_b32 s57, s56, 13
	s_add_u32 s64, s64, s57
	s_addc_u32 s65, s65, 0
	v_writelane_b32 v224, s64, 10
	v_writelane_b32 v224, s65, 11
	s_lshl_b32 s57, s56, 23
	s_add_u32 s50, s66, s57
	s_addc_u32 s51, s67, 0
	s_add_u32 s50, s50, 0x4900000
	s_addc_u32 s51, s51, 0
	v_writelane_b32 v224, s50, 12
	v_writelane_b32 v224, s51, 13
	s_lshl_b32 s57, s56, 23
	s_add_u32 s50, s66, s57
	s_addc_u32 s51, s67, 0
	s_add_u32 s50, s50, 0x16900000
	s_addc_u32 s51, s51, 0
	v_writelane_b32 v224, s50, 14
	v_writelane_b32 v224, s51, 15
	s_lshl_b32 s57, s56, 25
	s_add_u32 s50, s66, s57
	s_addc_u32 s51, s67, 0
	s_add_u32 s50, s50, 0xe900000
	s_addc_u32 s51, s51, 0
	v_writelane_b32 v224, s50, 16
	v_writelane_b32 v224, s51, 17
	s_lshl_b32 s57, s56, 25
	s_add_u32 s50, s66, s57
	s_addc_u32 s51, s67, 0
	s_add_u32 s50, s50, 0x6900000
	s_addc_u32 s51, s51, 0
	v_writelane_b32 v224, s50, 18
	v_writelane_b32 v224, s51, 19
	s_mov_b32 s53, 0
	s_load_dwordx2 s[14:15], s[28:29], 0xf0
	s_ashr_i32 s20, s0, 6
	s_ashr_i32 s21, s20, 31
	s_lshl_b32 s16, s0, 4
	s_lshl_b64 s[22:23], s[20:21], 12
	s_and_b32 s16, s16, 0x3c0
	s_waitcnt lgkmcnt(0)
	s_add_u32 s30, s14, 0x28700000
	s_addc_u32 s31, s15, 0
	s_load_dwordx2 s[18:19], s[28:29], 0x20
	s_load_dwordx4 s[44:47], s[28:29], 0x80
	s_add_u32 s34, s14, 0x31700000
	s_addc_u32 s35, s15, 0
	s_add_u32 s24, s14, 0x26700000
	v_readlane_b32 s26, v254, 22
	s_addc_u32 s25, s15, 0
	s_mov_b32 s48, s26
	s_mulk_i32 s26, 0x3480
	v_or_b32_e32 v46, s16, v161
	s_waitcnt lgkmcnt(0)
	s_add_u32 s18, s18, s26
	s_mul_hi_u32 s26, s48, 0x3480
	s_addc_u32 s19, s19, s26
	v_lshlrev_b32_e32 v156, 2, v46
	v_lshl_add_u64 v[0:1], s[18:19], 0, v[156:157]
	global_load_dwordx4 v[28:31], v156, s[18:19] offset:16
	global_load_dwordx4 v[8:11], v156, s[18:19]
	s_mov_b64 s[18:19], 0x1000
	v_lshl_add_u64 v[2:3], v[0:1], 0, s[18:19]
	v_add_co_u32_e32 v4, vcc, s69, v0
	s_mov_b64 s[18:19], 0x2000
	s_nop 0
	v_addc_co_u32_e32 v5, vcc, 0, v1, vcc
	v_lshl_add_u64 v[0:1], v[0:1], 0, s[18:19]
	s_add_u32 s18, s44, s6
	s_addc_u32 s19, s45, s7
	global_load_dwordx4 v[24:27], v[4:5], off offset:-4096
	global_load_dwordx4 v[32:35], v[4:5], off
	global_load_dwordx4 v[20:23], v[2:3], off offset:16
	global_load_dwordx4 v[36:39], v[0:1], off offset:16
	global_load_dwordx4 v[16:19], v156, s[18:19] offset:16
	global_load_dwordx4 v[12:15], v156, s[18:19]
	s_add_u32 s18, s46, s6
	s_addc_u32 s19, s47, s7
	v_lshl_add_u64 v[48:49], s[22:23], 0, v[120:121]
	v_mov_b64_e32 v[42:43], s[30:31]
	global_load_dwordx4 v[0:3], v156, s[18:19] offset:16
	global_load_dwordx4 v[4:7], v156, s[18:19]
	v_mad_u64_u32 v[44:45], s[18:19], v48, s75, v[42:43]
	v_lshl_add_u64 v[40:41], v[48:49], 0, v[122:123]
	v_mad_i32_i24 v45, v49, s75, v45
	v_lshlrev_b32_e32 v156, 1, v46
	v_lshl_add_u64 v[44:45], v[44:45], 0, v[156:157]
	v_mad_u64_u32 v[42:43], s[18:19], v40, s75, v[42:43]
	v_mad_i32_i24 v43, v41, s75, v43
	v_add_co_u32_e32 v40, vcc, s74, v44
	v_lshl_add_u64 v[46:47], v[42:43], 0, v[156:157]
	s_nop 0
	v_addc_co_u32_e32 v41, vcc, 0, v45, vcc
	global_load_dwordx4 v[88:91], v[40:41], off
	s_nop 0
	global_load_dwordx4 v[40:43], v[40:41], off offset:2048
	s_nop 0
	global_load_dwordx4 v[92:95], v[44:45], off offset:2048
	global_load_dwordx4 v[68:71], v[46:47], off offset:2048
	v_add_co_u32_e32 v44, vcc, s74, v46
	v_lshlrev_b64 v[144:145], 11, v[48:49]
	s_nop 0
	v_addc_co_u32_e32 v45, vcc, 0, v47, vcc
	global_load_dwordx4 v[64:67], v[44:45], off
	global_load_dwordx4 v[56:59], v[44:45], off offset:2048
	v_lshl_add_u64 v[44:45], s[34:35], 0, v[144:145]
	s_add_u32 s46, s14, 0x33700000
	v_lshl_add_u64 v[44:45], v[44:45], 0, v[156:157]
	s_addc_u32 s47, s15, 0
	global_load_dwordx4 v[60:63], v[44:45], off
	v_lshl_add_u64 v[44:45], s[46:47], 0, v[144:145]
	v_lshl_add_u64 v[44:45], v[44:45], 0, v[156:157]
	global_load_dwordx4 v[44:47], v[44:45], off
	v_cndmask_b32_e64 v50, 0, 1, s[2:3]
	v_cmp_ne_u32_e64 s[44:45], 1, v50
	s_andn2_b64 vcc, exec, s[2:3]
	v_readlane_b32 s27, v254, 23
	s_waitcnt vmcnt(1)
	v_mov_b64_e32 v[102:103], v[62:63]
	v_mov_b64_e32 v[106:107], v[62:63]
	v_mov_b64_e32 v[100:101], v[60:61]
	v_mov_b64_e32 v[104:105], v[60:61]
	s_cbranch_vccnz .LBB0_193
	v_lshlrev_b64 v[48:49], 10, v[48:49]
	v_lshlrev_b64 v[48:49], 1, v[48:49]
	v_lshl_add_u64 v[50:51], s[14:15], 0, v[48:49]
	v_lshl_add_u64 v[50:51], v[50:51], 0, v[156:157]
	v_add_co_u32_e32 v50, vcc, 0x37700000, v50
	v_lshl_add_u64 v[48:49], s[24:25], 0, v[48:49]
	s_nop 0
	v_addc_co_u32_e32 v51, vcc, 0, v51, vcc
	v_lshl_add_u64 v[48:49], v[48:49], 0, v[156:157]
	global_load_dwordx4 v[100:103], v[50:51], off
	global_load_dwordx4 v[104:107], v[48:49], off

.LBB0_208:
	s_mov_b32 s53, 0
	s_cmp_lt_u32 s55, 0xa000
	s_cbranch_scc0 .Lcis_a_done
	s_mov_b32 s53, 1
	s_cmp_lt_u32 s55, 0x1000
	s_cbranch_scc1 .Lcis_j_wout
	s_cmp_lt_u32 s55, 0x2000
	s_cbranch_scc1 .Lcis_j_gate
	s_cmp_lt_u32 s55, 0x6000
	s_cbranch_scc1 .Lcis_j_down
.Lcis_j_up:
	s_sub_u32 s51, s55, 0x6000
	s_lshr_b32 s50, s51, 8
	s_and_b32 s51, s51, 0xff
	s_movk_i32 s57, 15
	s_mov_b32 s60, 0x40000
	s_movk_i32 s61, 1
	s_movk_i32 s66, 12
	s_mov_b32 s67, 0x10000
	v_readlane_b32 s58, v224, 6
	v_readlane_b32 s59, v224, 7
	v_readlane_b32 s64, v224, 18
	v_readlane_b32 s65, v224, 19
	v_readlane_b32 s62, v224, 10
	v_readlane_b32 s63, v224, 11
	s_branch .Lcis_j_common
.Lcis_j_down:
	s_sub_u32 s51, s55, 0x2000
	s_lshr_b32 s50, s51, 6
	s_and_b32 s51, s51, 0x3f
	s_movk_i32 s57, 13
	s_mov_b32 s60, 0x10000
	s_movk_i32 s61, 0
	s_movk_i32 s66, 14
	s_mov_b32 s67, 0x40000
	v_readlane_b32 s58, v224, 4
	v_readlane_b32 s59, v224, 5
	v_readlane_b32 s64, v224, 16
	v_readlane_b32 s65, v224, 17
	s_branch .Lcis_j_common
.Lcis_j_gate:
	s_sub_u32 s51, s55, 0x1000
	s_lshr_b32 s50, s51, 6
	s_and_b32 s51, s51, 0x3f
	s_movk_i32 s57, 13
	s_mov_b32 s60, 0x10000
	s_movk_i32 s61, 1
	s_movk_i32 s66, 12
	s_mov_b32 s67, 0x10000
	v_readlane_b32 s58, v224, 2
	v_readlane_b32 s59, v224, 3
	v_readlane_b32 s64, v224, 14
	v_readlane_b32 s65, v224, 15
	v_readlane_b32 s62, v224, 8
	v_readlane_b32 s63, v224, 9
	s_branch .Lcis_j_common
.Lcis_j_wout:
	s_sub_u32 s51, s55, 0x0
	s_lshr_b32 s50, s51, 6
	s_and_b32 s51, s51, 0x3f
	s_movk_i32 s57, 13
	s_mov_b32 s60, 0x10000
	s_movk_i32 s61, 0
	s_movk_i32 s66, 12
	s_mov_b32 s67, 0x10000
	v_readlane_b32 s58, v224, 0
	v_readlane_b32 s59, v224, 1
	v_readlane_b32 s64, v224, 12
	v_readlane_b32 s65, v224, 13
.Lcis_j_common:
	s_add_u32 s52, s57, 5
	s_lshl_b32 s52, s50, s52
	s_add_u32 s58, s58, s52
	s_addc_u32 s59, s59, 0
	s_lshl_b32 s52, s51, 7
	s_add_u32 s58, s58, s52
	s_addc_u32 s59, s59, 0
	s_add_u32 s52, s66, 5
	s_lshl_b32 s52, s51, s52
	s_add_u32 s64, s64, s52
	s_addc_u32 s65, s65, 0
	s_lshl_b32 s52, s50, 6
	s_add_u32 s64, s64, s52
	s_addc_u32 s65, s65, 0
	v_lshrrev_b32_e32 v222, 3, v197
	v_and_b32_e32 v223, 7, v197
	v_lshlrev_b32_e32 v216, s57, v222
	v_lshl_add_u32 v216, v223, 4, v216
	global_load_dwordx4 v[232:235], v216, s[58:59]
	s_add_u32 s58, s58, s60
	s_addc_u32 s59, s59, 0
	global_load_dwordx4 v[236:239], v216, s[58:59]
	s_add_u32 s58, s58, s60
	s_addc_u32 s59, s59, 0
	global_load_dwordx4 v[240:243], v216, s[58:59]
	s_add_u32 s58, s58, s60
	s_addc_u32 s59, s59, 0
	global_load_dwordx4 v[244:247], v216, s[58:59]
	s_cmp_eq_u32 s61, 0
	s_cbranch_scc1 .Lcis_a_done
	s_lshl_b32 s52, s50, 7
	s_add_u32 s62, s62, s52
	s_addc_u32 s63, s63, 0
	global_load_dword v248, v217, s[62:63] offset:0
	global_load_dword v249, v217, s[62:63] offset:32
	global_load_dword v250, v217, s[62:63] offset:64
	global_load_dword v251, v217, s[62:63] offset:96

.LBB0_212:
	s_or_b64 exec, exec, s[22:23]
	s_and_b32 s22, s24, 0x800
	s_addk_i32 s24, 0x800
	v_add_u32_e32 v40, s22, v171
	s_add_u32 s20, s20, 32
	ds_read_b64 v[40:41], v40
	s_addc_u32 s21, s21, 0
	s_mov_b64 s[22:23], 0x48000
	s_add_i32 s19, s19, 1
	s_waitcnt lgkmcnt(0)
	v_cvt_pk_bf16_f32 v42, v40, v41
	v_lshl_add_u64 v[40:41], s[14:15], 0, v[148:149]
	v_lshl_add_u64 v[148:149], v[148:149], 0, s[92:93]
	v_lshl_add_u64 v[150:151], v[150:151], 0, s[92:93]
	v_lshl_add_u64 v[154:155], v[154:155], 0, s[22:23]
	s_cmp_eq_u32 s53, 1
	s_cbranch_scc0 .Lcis_b_done
	s_waitcnt vmcnt(0)
	s_cmp_eq_u32 s61, 0
	s_cbranch_scc1 .Lcis_b_nogs
	v_mul_f32_e32 v232, v232, v248
	v_mul_f32_e32 v233, v233, v248
	v_mul_f32_e32 v234, v234, v248
	v_mul_f32_e32 v235, v235, v248
	v_mul_f32_e32 v236, v236, v249
	v_mul_f32_e32 v237, v237, v249
	v_mul_f32_e32 v238, v238, v249
	v_mul_f32_e32 v239, v239, v249
	v_mul_f32_e32 v240, v240, v250
	v_mul_f32_e32 v241, v241, v250
	v_mul_f32_e32 v242, v242, v250
	v_mul_f32_e32 v243, v243, v250
	v_mul_f32_e32 v244, v244, v251
	v_mul_f32_e32 v245, v245, v251
	v_mul_f32_e32 v246, v246, v251
	v_mul_f32_e32 v247, v247, v251
.Lcis_b_nogs:
	ds_write_b32 v218, v232 offset:0
	ds_write_b32 v218, v233 offset:4
	ds_write_b32 v218, v234 offset:8
	ds_write_b32 v218, v235 offset:12
	ds_write_b32 v218, v236 offset:1056
	ds_write_b32 v218, v237 offset:1060
	ds_write_b32 v218, v238 offset:1064
	ds_write_b32 v218, v239 offset:1068
	ds_write_b32 v218, v240 offset:2112
	ds_write_b32 v218, v241 offset:2116
	ds_write_b32 v218, v242 offset:2120
	ds_write_b32 v218, v243 offset:2124
	ds_write_b32 v218, v244 offset:3168
	ds_write_b32 v218, v245 offset:3172
	ds_write_b32 v218, v246 offset:3176
	ds_write_b32 v218, v247 offset:3180
	v_lshrrev_b32_e32 v222, 2, v197
	v_and_b32_e32 v223, 3, v197
	v_lshlrev_b32_e32 v220, s66, v222
	v_lshl_add_u32 v220, v223, 4, v220
	s_waitcnt lgkmcnt(0)
	ds_read2_b32 v[208:209], v219 offset0:0 offset1:33
	ds_read2_b32 v[210:211], v219 offset0:66 offset1:99
	ds_read2_b32 v[212:213], v219 offset0:132 offset1:165
	ds_read2_b32 v[214:215], v219 offset0:198 offset1:231
	s_waitcnt lgkmcnt(0)
	v_cvt_pk_bf16_f32 v208, v208, v209
	v_cvt_pk_bf16_f32 v209, v210, v211
	v_cvt_pk_bf16_f32 v210, v212, v213
	v_cvt_pk_bf16_f32 v211, v214, v215
	global_store_dwordx4 v220, v[208:211], s[64:65]
	s_add_u32 s64, s64, s67
	s_addc_u32 s65, s65, 0
	ds_read2_b32 v[208:209], v219 offset0:16 offset1:49
	ds_read2_b32 v[210:211], v219 offset0:82 offset1:115
	ds_read2_b32 v[212:213], v219 offset0:148 offset1:181
	ds_read2_b32 v[214:215], v219 offset0:214 offset1:247
	s_waitcnt lgkmcnt(0)
	v_cvt_pk_bf16_f32 v208, v208, v209
	v_cvt_pk_bf16_f32 v209, v210, v211
	v_cvt_pk_bf16_f32 v210, v212, v213
	v_cvt_pk_bf16_f32 v211, v214, v215
	global_store_dwordx4 v220, v[208:211], s[64:65]
	s_lshl_b32 s50, s80, 2
	s_add_u32 s55, s55, s50
.Lcis_b_done:
	s_cmpk_eq_i32 s20, 0xfa0
	global_store_dword v[40:41], v42, off
	s_barrier
	s_cbranch_scc1 .LBB0_214
	s_waitcnt vmcnt(1)
	v_mov_b64_e32 v[92:93], v[108:109]
	v_mov_b64_e32 v[88:89], v[96:97]
	v_mov_b64_e32 v[40:41], v[48:49]
	v_mov_b64_e32 v[44:45], v[52:53]
	v_mov_b64_e32 v[104:105], v[116:117]
	v_mov_b64_e32 v[100:101], v[112:113]
	v_mov_b64_e32 v[56:57], v[72:73]
	v_mov_b64_e32 v[64:65], v[76:77]
	v_mov_b64_e32 v[60:61], v[84:85]
	v_mov_b64_e32 v[68:69], v[80:81]
	v_mov_b64_e32 v[94:95], v[110:111]
	v_mov_b64_e32 v[90:91], v[98:99]
	v_mov_b64_e32 v[42:43], v[50:51]
	v_mov_b64_e32 v[46:47], v[54:55]
	v_mov_b64_e32 v[106:107], v[118:119]
	v_mov_b64_e32 v[102:103], v[114:115]
	v_mov_b64_e32 v[58:59], v[74:75]
	v_mov_b64_e32 v[66:67], v[78:79]
	v_mov_b64_e32 v[62:63], v[86:87]
	v_mov_b64_e32 v[70:71], v[82:83]
	s_branch .LBB0_206
